# prep x/mem -> bf16 conversion hand-written: unrolled, two iterations of loads in flight (compiler loop had three serial round trips per iteration)
# speedup vs baseline: 1.0013x; 1.0013x over previous
; __device__ __forceinline__ unsigned cvt_pk(float lo, float hi) { const f32x2 v = {lo, hi}; const bf16x2_t b = __builtin_convertvector(v, bf16x2_t); return __builtin_bit_cast(unsigned, b); }
; __device__ __forceinline__ void phase_prep(const Params& p, LAS unsigned char* lds) {
;     ...
;     const int NCH_X = NTOK * DM / 8, NCH_M = 1024 * 2048 / 8, NCH = NCH_X + NCH_M;
;     for (int ch0 = (blockIdx.x * 512 + tid); ch0 < NCH; ch0 += gridDim.x * 512 * 4) {
;       f32x4 a[4], b[4];
; #pragma unroll
;       for (int q = 0; q < 4; ++q) {
;         const int ch = ch0 + q * (int)gridDim.x * 512;
;         if (ch < NCH) {
;           const float* src = ch < TOKP * DM / 8 ? p.in[0] + (size_t)ch * 8 : ch < NCH_X ? p.in[1] + (size_t)(ch - TOKP * DM / 8) * 8 : p.in[2] + (size_t)(ch - NCH_X) * 8;
;           a[q] = __builtin_nontemporal_load((const f32x4*)src); b[q] = __builtin_nontemporal_load((const f32x4*)(src + 4));
;         }
;       }
; #pragma unroll
;       for (int q = 0; q < 4; ++q) {
;         const int ch = ch0 + q * (int)gridDim.x * 512;
;         if (ch < NCH) {
;           bf16_t* dst = ch < NCH_X ? (bf16_t*)(ws + WS_XB) + (size_t)ch * 8 : (bf16_t*)(ws + WS_MEMB) + (size_t)(ch - NCH_X) * 8;
;           u32x4 o; o[0] = cvt_pk(a[q][0], a[q][1]); o[1] = cvt_pk(a[q][2], a[q][3]); o[2] = cvt_pk(b[q][0], b[q][1]); o[3] = cvt_pk(b[q][2], b[q][3]);
;           *(u32x4*)dst = o;
;         }
;       }
;     }
.LBB0_1574:
	s_or_b64 exec, exec, s[38:39]
	s_mov_b32 s29, 0x280000
	v_cmp_gt_i32_e32 vcc, s29, v4
	s_and_saveexec_b64 s[42:43], vcc
	s_cbranch_execz .LBB0_1621
	s_cmp_lg_u32 s28, 0x100
	s_cbranch_scc1 .Lxc_orig
	v_readlane_b32 s29, v255, 11
	v_readlane_b32 s38, v254, 30
	v_readlane_b32 s39, v254, 31
	v_readlane_b32 s40, v253, 43
	v_readlane_b32 s41, v253, 44
	s_nop 1
	v_add_u32_e32 v96, s29, v66
	v_lshlrev_b32_e32 v97, 4, v96
	v_lshlrev_b32_e32 v96, 5, v96
	s_add_u32 s34, s4, 0x0
	s_addc_u32 s35, s5, 0
	global_load_dwordx4 v[100:103], v96, s[34:35] nt
	global_load_dwordx4 v[104:107], v96, s[34:35] offset:16 nt
	s_add_u32 s34, s4, 0x400000
	s_addc_u32 s35, s5, 0
	global_load_dwordx4 v[108:111], v96, s[34:35] nt
	global_load_dwordx4 v[112:115], v96, s[34:35] offset:16 nt
	s_add_u32 s34, s4, 0x800000
	s_addc_u32 s35, s5, 0
	global_load_dwordx4 v[116:119], v96, s[34:35] nt
	global_load_dwordx4 v[120:123], v96, s[34:35] offset:16 nt
	s_add_u32 s34, s4, 0xc00000
	s_addc_u32 s35, s5, 0
	global_load_dwordx4 v[124:127], v96, s[34:35] nt
	global_load_dwordx4 v[128:131], v96, s[34:35] offset:16 nt
	s_add_u32 s34, s4, 0x1000000
	s_addc_u32 s35, s5, 0
	global_load_dwordx4 v[132:135], v96, s[34:35] nt
	global_load_dwordx4 v[136:139], v96, s[34:35] offset:16 nt
	s_add_u32 s34, s4, 0x1400000
	s_addc_u32 s35, s5, 0
	global_load_dwordx4 v[140:143], v96, s[34:35] nt
	global_load_dwordx4 v[144:147], v96, s[34:35] offset:16 nt
	s_add_u32 s34, s4, 0x1800000
	s_addc_u32 s35, s5, 0
	global_load_dwordx4 v[148:151], v96, s[34:35] nt
	global_load_dwordx4 v[152:155], v96, s[34:35] offset:16 nt
	s_add_u32 s34, s4, 0x1c00000
	s_addc_u32 s35, s5, 0
	global_load_dwordx4 v[156:159], v96, s[34:35] nt
	global_load_dwordx4 v[160:163], v96, s[34:35] offset:16 nt
	s_waitcnt vmcnt(14)
	v_cvt_pk_bf16_f32 v100, v100, v101
	v_cvt_pk_bf16_f32 v101, v102, v103
	v_cvt_pk_bf16_f32 v102, v104, v105
	v_cvt_pk_bf16_f32 v103, v106, v107
	s_add_u32 s36, s38, 0x0
	s_addc_u32 s37, s39, 0
	global_store_dwordx4 v97, v[100:103], s[36:37]
	s_waitcnt vmcnt(13)
	v_cvt_pk_bf16_f32 v108, v108, v109
	v_cvt_pk_bf16_f32 v109, v110, v111
	v_cvt_pk_bf16_f32 v110, v112, v113
	v_cvt_pk_bf16_f32 v111, v114, v115
	s_add_u32 s36, s38, 0x200000
	s_addc_u32 s37, s39, 0
	global_store_dwordx4 v97, v[108:111], s[36:37]
	s_waitcnt vmcnt(12)
	v_cvt_pk_bf16_f32 v116, v116, v117
	v_cvt_pk_bf16_f32 v117, v118, v119
	v_cvt_pk_bf16_f32 v118, v120, v121
	v_cvt_pk_bf16_f32 v119, v122, v123
	s_add_u32 s36, s38, 0x400000
	s_addc_u32 s37, s39, 0
	global_store_dwordx4 v97, v[116:119], s[36:37]
	s_waitcnt vmcnt(11)
	v_cvt_pk_bf16_f32 v124, v124, v125
	v_cvt_pk_bf16_f32 v125, v126, v127
	v_cvt_pk_bf16_f32 v126, v128, v129
	v_cvt_pk_bf16_f32 v127, v130, v131
	s_add_u32 s36, s38, 0x600000
	s_addc_u32 s37, s39, 0
	global_store_dwordx4 v97, v[124:127], s[36:37]
	s_add_u32 s34, s4, 0x2000000
	s_addc_u32 s35, s5, 0
	global_load_dwordx4 v[100:103], v96, s[34:35] nt
	global_load_dwordx4 v[104:107], v96, s[34:35] offset:16 nt
	s_add_u32 s34, s4, 0x2400000
	s_addc_u32 s35, s5, 0
	global_load_dwordx4 v[108:111], v96, s[34:35] nt
	global_load_dwordx4 v[112:115], v96, s[34:35] offset:16 nt
	s_add_u32 s34, s4, 0x2800000
	s_addc_u32 s35, s5, 0
	global_load_dwordx4 v[116:119], v96, s[34:35] nt
	global_load_dwordx4 v[120:123], v96, s[34:35] offset:16 nt
	s_add_u32 s34, s4, 0x2c00000
	s_addc_u32 s35, s5, 0
	global_load_dwordx4 v[124:127], v96, s[34:35] nt
	global_load_dwordx4 v[128:131], v96, s[34:35] offset:16 nt
	s_waitcnt vmcnt(18)
	v_cvt_pk_bf16_f32 v132, v132, v133
	v_cvt_pk_bf16_f32 v133, v134, v135
	v_cvt_pk_bf16_f32 v134, v136, v137
	v_cvt_pk_bf16_f32 v135, v138, v139
	s_add_u32 s36, s38, 0x800000
	s_addc_u32 s37, s39, 0
	global_store_dwordx4 v97, v[132:135], s[36:37]
	s_waitcnt vmcnt(17)
	v_cvt_pk_bf16_f32 v140, v140, v141
	v_cvt_pk_bf16_f32 v141, v142, v143
	v_cvt_pk_bf16_f32 v142, v144, v145
	v_cvt_pk_bf16_f32 v143, v146, v147
	s_add_u32 s36, s38, 0xa00000
	s_addc_u32 s37, s39, 0
	global_store_dwordx4 v97, v[140:143], s[36:37]
	s_waitcnt vmcnt(16)
	v_cvt_pk_bf16_f32 v148, v148, v149
	v_cvt_pk_bf16_f32 v149, v150, v151
	v_cvt_pk_bf16_f32 v150, v152, v153
	v_cvt_pk_bf16_f32 v151, v154, v155
	s_add_u32 s36, s38, 0xc00000
	s_addc_u32 s37, s39, 0
	global_store_dwordx4 v97, v[148:151], s[36:37]
	s_waitcnt vmcnt(15)
	v_cvt_pk_bf16_f32 v156, v156, v157
	v_cvt_pk_bf16_f32 v157, v158, v159
	v_cvt_pk_bf16_f32 v158, v160, v161
	v_cvt_pk_bf16_f32 v159, v162, v163
	s_add_u32 s36, s38, 0xe00000
	s_addc_u32 s37, s39, 0
	global_store_dwordx4 v97, v[156:159], s[36:37]
	s_add_u32 s34, s4, 0x3000000
	s_addc_u32 s35, s5, 0
	global_load_dwordx4 v[132:135], v96, s[34:35] nt
	global_load_dwordx4 v[136:139], v96, s[34:35] offset:16 nt
	s_add_u32 s34, s4, 0x3400000
	s_addc_u32 s35, s5, 0
	global_load_dwordx4 v[140:143], v96, s[34:35] nt
	global_load_dwordx4 v[144:147], v96, s[34:35] offset:16 nt
	s_add_u32 s34, s4, 0x3800000
	s_addc_u32 s35, s5, 0
	global_load_dwordx4 v[148:151], v96, s[34:35] nt
	global_load_dwordx4 v[152:155], v96, s[34:35] offset:16 nt
	s_add_u32 s34, s4, 0x3c00000
	s_addc_u32 s35, s5, 0
	global_load_dwordx4 v[156:159], v96, s[34:35] nt
	global_load_dwordx4 v[160:163], v96, s[34:35] offset:16 nt
	s_waitcnt vmcnt(18)
; __device__ __forceinline__ unsigned cvt_pk(float lo, float hi) { const f32x2 v = {lo, hi}; const bf16x2_t b = __builtin_convertvector(v, bf16x2_t); return __builtin_bit_cast(unsigned, b); }
; __device__ __forceinline__ void phase_prep(const Params& p, LAS unsigned char* lds) {
;     ...
;     const int NCH_X = NTOK * DM / 8, NCH_M = 1024 * 2048 / 8, NCH = NCH_X + NCH_M;
;     for (int ch0 = (blockIdx.x * 512 + tid); ch0 < NCH; ch0 += gridDim.x * 512 * 4) {
;       f32x4 a[4], b[4];
; #pragma unroll
;       for (int q = 0; q < 4; ++q) {
;         const int ch = ch0 + q * (int)gridDim.x * 512;
;         if (ch < NCH) {
;           const float* src = ch < TOKP * DM / 8 ? p.in[0] + (size_t)ch * 8 : ch < NCH_X ? p.in[1] + (size_t)(ch - TOKP * DM / 8) * 8 : p.in[2] + (size_t)(ch - NCH_X) * 8;
;           a[q] = __builtin_nontemporal_load((const f32x4*)src); b[q] = __builtin_nontemporal_load((const f32x4*)(src + 4));
;         }
;       }
; #pragma unroll
;       for (int q = 0; q < 4; ++q) {
;         const int ch = ch0 + q * (int)gridDim.x * 512;
;         if (ch < NCH) {
;           bf16_t* dst = ch < NCH_X ? (bf16_t*)(ws + WS_XB) + (size_t)ch * 8 : (bf16_t*)(ws + WS_MEMB) + (size_t)(ch - NCH_X) * 8;
;           u32x4 o; o[0] = cvt_pk(a[q][0], a[q][1]); o[1] = cvt_pk(a[q][2], a[q][3]); o[2] = cvt_pk(b[q][0], b[q][1]); o[3] = cvt_pk(b[q][2], b[q][3]);
;           *(u32x4*)dst = o;
;         }
;       }
;     }
	v_cvt_pk_bf16_f32 v100, v100, v101
	v_cvt_pk_bf16_f32 v101, v102, v103
	v_cvt_pk_bf16_f32 v102, v104, v105
	v_cvt_pk_bf16_f32 v103, v106, v107
	s_add_u32 s36, s38, 0x1000000
	s_addc_u32 s37, s39, 0
	global_store_dwordx4 v97, v[100:103], s[36:37]
	s_waitcnt vmcnt(17)
	v_cvt_pk_bf16_f32 v108, v108, v109
	v_cvt_pk_bf16_f32 v109, v110, v111
	v_cvt_pk_bf16_f32 v110, v112, v113
	v_cvt_pk_bf16_f32 v111, v114, v115
	s_add_u32 s36, s38, 0x1200000
	s_addc_u32 s37, s39, 0
	global_store_dwordx4 v97, v[108:111], s[36:37]
	s_waitcnt vmcnt(16)
	v_cvt_pk_bf16_f32 v116, v116, v117
	v_cvt_pk_bf16_f32 v117, v118, v119
	v_cvt_pk_bf16_f32 v118, v120, v121
	v_cvt_pk_bf16_f32 v119, v122, v123
	s_add_u32 s36, s38, 0x1400000
	s_addc_u32 s37, s39, 0
	global_store_dwordx4 v97, v[116:119], s[36:37]
	s_waitcnt vmcnt(15)
	v_cvt_pk_bf16_f32 v124, v124, v125
	v_cvt_pk_bf16_f32 v125, v126, v127
	v_cvt_pk_bf16_f32 v126, v128, v129
	v_cvt_pk_bf16_f32 v127, v130, v131
	s_add_u32 s36, s38, 0x1600000
	s_addc_u32 s37, s39, 0
	global_store_dwordx4 v97, v[124:127], s[36:37]
	s_add_u32 s34, s6, 0x0
	s_addc_u32 s35, s7, 0
	global_load_dwordx4 v[100:103], v96, s[34:35] nt
	global_load_dwordx4 v[104:107], v96, s[34:35] offset:16 nt
	s_add_u32 s34, s6, 0x400000
	s_addc_u32 s35, s7, 0
	global_load_dwordx4 v[108:111], v96, s[34:35] nt
	global_load_dwordx4 v[112:115], v96, s[34:35] offset:16 nt
	s_add_u32 s34, s8, 0x0
	s_addc_u32 s35, s9, 0
	global_load_dwordx4 v[116:119], v96, s[34:35] nt
	global_load_dwordx4 v[120:123], v96, s[34:35] offset:16 nt
	s_add_u32 s34, s8, 0x400000
	s_addc_u32 s35, s9, 0
	global_load_dwordx4 v[124:127], v96, s[34:35] nt
	global_load_dwordx4 v[128:131], v96, s[34:35] offset:16 nt
	s_waitcnt vmcnt(18)
	v_cvt_pk_bf16_f32 v132, v132, v133
	v_cvt_pk_bf16_f32 v133, v134, v135
	v_cvt_pk_bf16_f32 v134, v136, v137
	v_cvt_pk_bf16_f32 v135, v138, v139
	s_add_u32 s36, s38, 0x1800000
	s_addc_u32 s37, s39, 0
	global_store_dwordx4 v97, v[132:135], s[36:37]
	s_waitcnt vmcnt(17)
	v_cvt_pk_bf16_f32 v140, v140, v141
	v_cvt_pk_bf16_f32 v141, v142, v143
	v_cvt_pk_bf16_f32 v142, v144, v145
	v_cvt_pk_bf16_f32 v143, v146, v147
	s_add_u32 s36, s38, 0x1a00000
	s_addc_u32 s37, s39, 0
	global_store_dwordx4 v97, v[140:143], s[36:37]
	s_waitcnt vmcnt(16)
	v_cvt_pk_bf16_f32 v148, v148, v149
	v_cvt_pk_bf16_f32 v149, v150, v151
	v_cvt_pk_bf16_f32 v150, v152, v153
	v_cvt_pk_bf16_f32 v151, v154, v155
	s_add_u32 s36, s38, 0x1c00000
	s_addc_u32 s37, s39, 0
	global_store_dwordx4 v97, v[148:151], s[36:37]
	s_waitcnt vmcnt(15)
	v_cvt_pk_bf16_f32 v156, v156, v157
	v_cvt_pk_bf16_f32 v157, v158, v159
	v_cvt_pk_bf16_f32 v158, v160, v161
	v_cvt_pk_bf16_f32 v159, v162, v163
	s_add_u32 s36, s38, 0x1e00000
	s_addc_u32 s37, s39, 0
	global_store_dwordx4 v97, v[156:159], s[36:37]
	s_waitcnt vmcnt(10)
	v_cvt_pk_bf16_f32 v100, v100, v101
	v_cvt_pk_bf16_f32 v101, v102, v103
	v_cvt_pk_bf16_f32 v102, v104, v105
	v_cvt_pk_bf16_f32 v103, v106, v107
	s_add_u32 s36, s38, 0x2000000
	s_addc_u32 s37, s39, 0
	global_store_dwordx4 v97, v[100:103], s[36:37]
	s_waitcnt vmcnt(9)
	v_cvt_pk_bf16_f32 v108, v108, v109
	v_cvt_pk_bf16_f32 v109, v110, v111
	v_cvt_pk_bf16_f32 v110, v112, v113
	v_cvt_pk_bf16_f32 v111, v114, v115
	s_add_u32 s36, s38, 0x2200000
	s_addc_u32 s37, s39, 0
	global_store_dwordx4 v97, v[108:111], s[36:37]
	s_waitcnt vmcnt(8)
	v_cvt_pk_bf16_f32 v116, v116, v117
	v_cvt_pk_bf16_f32 v117, v118, v119
	v_cvt_pk_bf16_f32 v118, v120, v121
	v_cvt_pk_bf16_f32 v119, v122, v123
	s_add_u32 s36, s40, 0x0
	s_addc_u32 s37, s41, 0
	global_store_dwordx4 v97, v[116:119], s[36:37]
	s_waitcnt vmcnt(7)
	v_cvt_pk_bf16_f32 v124, v124, v125
	v_cvt_pk_bf16_f32 v125, v126, v127
	v_cvt_pk_bf16_f32 v126, v128, v129
	v_cvt_pk_bf16_f32 v127, v130, v131
	s_add_u32 s36, s40, 0x200000
	s_addc_u32 s37, s41, 0
	global_store_dwordx4 v97, v[124:127], s[36:37]
	s_branch .LBB0_1621
.Lxc_orig:
	v_readlane_b32 s29, v255, 12
	v_mov_b32_e32 v4, 0
	s_mov_b64 s[44:45], 0
	v_add_u32_e32 v68, s29, v66
	v_mov_b32_e32 v5, v4
	v_mov_b32_e32 v6, v4
	v_mov_b32_e32 v7, v4
	v_mov_b32_e32 v8, v4
	v_mov_b32_e32 v9, v4
	v_mov_b32_e32 v10, v4
	v_mov_b32_e32 v11, v4
	v_mov_b32_e32 v12, v4
	v_mov_b32_e32 v13, v4
	v_mov_b32_e32 v14, v4
	v_mov_b32_e32 v15, v4
	v_mov_b32_e32 v20, v4
	v_mov_b32_e32 v21, v4
	v_mov_b32_e32 v22, v4
	v_mov_b32_e32 v23, v4
	v_mov_b32_e32 v24, v4
	v_mov_b32_e32 v25, v4
	v_mov_b32_e32 v26, v4
	v_mov_b32_e32 v27, v4
	v_mov_b32_e32 v28, v4
	v_mov_b32_e32 v29, v4
	v_mov_b32_e32 v30, v4
	v_mov_b32_e32 v31, v4
	s_branch .LBB0_1577
